# cacheconv on all WGs + up-GEMM column tiles visited in reverse order (H low-K columns written last) + up-GEMM K-loop LDS-DMA addresses in scalar-base form (no 64-bit VALU adds)
# speedup vs baseline: 1.0010x; 1.0010x over previous
; DI int launder_tid() { int t = threadIdx.x; asm volatile("" : "+v"(t)); return t; }
; #define PG8_STAGE(bufoff, gbase, voff) do { _Pragma("unroll") for (int _i = 0; _i < 2; ++_i) \
;         __builtin_amdgcn_global_load_lds((const unsigned*)((const char*)(gbase) + (voff)[_i]), (LAS unsigned*)(lds + (bufoff) + ldsw + _i * 8192), 16, 0, 0); } while (0)
; #define PG8_WAIT_V(n) asm volatile("s_waitcnt vmcnt(" #n ")" ::: "memory")
; #define PG8_BAR __builtin_amdgcn_s_barrier()
; template <class Epi, class Sched>
; DI void gemm_phase(LAS unsigned char* lds, const Sched& S, const Epi& E) {
;     const int tid = launder_tid(), wid = __builtin_amdgcn_readfirstlane(tid >> 6), lane = tid & 63, wr = wid >> 2, wc = wid & 3, fr = lane & 15, fq = lane >> 4;
;     const int lda = S.g.lda, ldb = S.g.ldb;
;     unsigned voffA[2], voffB[2];
; #pragma unroll
;     for (int i = 0; i < 2; ++i) { int R, C; stage_rc(tid * 16 + i * 8192, R, C); const int Rb = (R & ~31) + perm32(R & 31);
;         voffA[i] = (unsigned)(R * lda + C) * 2u; voffB[i] = (unsigned)(Rb * ldb + C) * 2u; }
;     const size_t kstep = (size_t)(BK * 2);
;     const size_t hstepA = (size_t)HALF * lda * 2, hstepB = (size_t)HALF * ldb * 2;
;     const unsigned ldsw = (unsigned)wid * 1024u;
;     const int aoff = lds_byte(wr * 64 + fr, fq * 8), boff = lds_byte(wc * 32 + fr, fq * 8);
;     ...
;     Unit cur, nxt; int ui = 0;
;     if (!S.next(0, cur)) return;
;     f32x4 acc[2][2][4][2];
; #pragma unroll
;     for (int a = 0; a < 2; ++a)
; #pragma unroll
;         for (int b = 0; b < 2; ++b)
; #pragma unroll
;             for (int m = 0; m < 4; ++m)
; #pragma unroll
;                 for (int n = 0; n < 2; ++n) acc[a][b][m][n] = (f32x4){0.f, 0.f, 0.f, 0.f};
;     bf16x8 At[4][2], B0[2][2], B1[2][2];
;     const char* cA = cur.a; const char* cB = cur.b;
;     ...
;     PG8_RSDMA(cur, 0);
;     PG8_STAGE(PG8_SB(0, 0), cB, voffB); PG8_STAGE(PG8_SB(0, 1), cB + hstepB, voffB); PG8_STAGE(PG8_SA(0, 0), cA, voffA); PG8_STAGE(PG8_SA(0, 1), cA + hstepA, voffA);
;     if (wr == 1) PG8_BAR;
;     PG8_WAIT_V(2); PG8_BAR;
;     PG8_STAGE(PG8_SB(1, 0), cB + kstep, voffB); PG8_STAGE(PG8_SA(1, 0), cA + kstep, voffA); PG8_STAGE(PG8_SB(1, 1), cB + hstepB + kstep, voffB);
;     PG8_WAIT_V(6); PG8_BAR;
.LBB0_1382:
	v_ashrrev_i32_e32 v2, 31, v5
	v_lshrrev_b32_e32 v2, 26, v2
	v_add_u32_e32 v2, v5, v2
	v_ashrrev_i32_e32 v14, 6, v2
	v_bfe_i32 v2, v5, 27, 1
	v_lshlrev_b32_e32 v1, 4, v5
	v_lshrrev_b32_e32 v2, 22, v2
	v_add_u32_e32 v2, v1, v2
	v_readlane_b32 s26, v252, 15
	v_and_b32_e32 v2, 0xfffffc00, v2
	v_readlane_b32 s27, v252, 16
	v_sub_u32_e32 v2, v1, v2
	s_add_u32 s12, s34, 0x21c56000
	s_mov_b32 s27, s13
	v_lshrrev_b32_e32 v6, 4, v2
	s_addc_u32 s22, s35, 0
	s_mov_b32 s34, s26
	s_lshl_b64 s[26:27], s[26:27], 1
	v_bitop3_b32 v6, v6, v2, 32 bitop3:0x6c
	v_ashrrev_i32_e32 v2, 31, v2
	s_add_u32 s8, s8, s26
	v_lshrrev_b32_e32 v2, 26, v2
	s_addc_u32 s9, s9, s27
	v_add_u32_e32 v2, v6, v2
	s_add_u32 s23, s8, 0x4a56000
	v_ashrrev_i32_e32 v15, 6, v2
	s_addc_u32 s26, s9, 0
	v_readlane_b32 s8, v254, 46
	v_lshlrev_b32_e32 v7, 3, v14
	v_mul_i32_i24_e32 v8, 64, v15
	v_readlane_b32 s9, v254, 47
	s_add_u32 s48, s12, s8
	v_and_b32_e32 v7, -16, v7
	v_sub_u32_e32 v6, v6, v8
	s_addc_u32 s49, s22, s9
	v_readlane_b32 s8, v254, 50
	s_sub_i32 s8, 0x1f00000, s8
	v_add_u32_e32 v2, v15, v7
	v_ashrrev_i16_sdwa v6, v218, sext(v6) dst_sel:DWORD dst_unused:UNUSED_PAD src0_sel:DWORD src1_sel:BYTE_0
	s_add_u32 s50, s23, s8
	v_lshlrev_b32_e32 v7, 5, v14
	v_bfe_i32 v16, v6, 0, 16
	v_lshlrev_b32_e32 v6, 1, v2
	v_lshrrev_b32_e32 v8, 2, v2
	v_and_b32_e32 v9, 3, v15
	s_mov_b32 s8, 0xfffe0
	v_and_b32_e32 v7, 32, v7
	v_and_b32_e32 v6, 24, v6
	v_and_b32_e32 v8, 4, v8
	v_and_or_b32 v9, v2, s8, v9
	v_or3_b32 v6, v9, v8, v6
	v_add_lshl_u32 v7, v7, v16, 1
	v_add_u32_e32 v1, 0x2000, v1
	v_lshl_add_u32 v132, v2, 12, v7
	v_lshl_add_u32 v2, v6, 12, v7
	v_ashrrev_i32_e32 v6, 31, v1
	v_lshrrev_b32_e32 v6, 22, v6
	v_add_u32_e32 v6, v1, v6
	v_ashrrev_i32_e32 v17, 10, v6
	v_mul_i32_i24_e32 v6, 0x400, v17
	v_sub_u32_e32 v1, v1, v6
	v_lshrrev_b32_e32 v6, 4, v1
	v_bitop3_b32 v1, v6, v1, 32 bitop3:0x6c
	v_ashrrev_i32_e32 v7, 31, v1
	v_lshrrev_b32_e32 v7, 26, v7
	v_add_u32_e32 v7, v1, v7
	v_lshlrev_b32_e32 v6, 3, v17
	v_ashrrev_i32_e32 v18, 6, v7
	v_and_b32_e32 v7, 0xc0, v7
	v_readlane_b32 s9, v254, 51
	v_and_b32_e32 v6, -16, v6
	v_sub_u32_e32 v1, v1, v7
	s_addc_u32 s51, s26, s9
	v_add_u32_e32 v6, v18, v6
	v_ashrrev_i16_sdwa v1, v218, sext(v1) dst_sel:DWORD dst_unused:UNUSED_PAD src0_sel:DWORD src1_sel:BYTE_0
	s_lshl_b32 s27, s38, 10
	v_lshlrev_b32_e32 v8, 5, v17
	v_bfe_i32 v19, v1, 0, 16
	v_lshlrev_b32_e32 v1, 1, v6
	v_lshrrev_b32_e32 v7, 2, v6
	v_and_b32_e32 v9, 3, v18
	s_add_i32 s54, s27, 0
	v_writelane_b32 v252, s34, 15
	v_and_b32_e32 v8, 32, v8
	v_and_b32_e32 v1, 24, v1
	v_and_b32_e32 v7, 4, v7
	v_and_or_b32 v9, v6, s8, v9
	s_add_i32 m0, s54, 0x10000
	v_writelane_b32 v252, s35, 16
	s_ashr_i32 s34, s41, 8
	v_or3_b32 v1, v9, v7, v1
	v_add_lshl_u32 v7, v8, v19, 1
	global_load_lds_dwordx4 v2, s[50:51]
	s_add_i32 m0, s54, 0x12000
	s_waitcnt vmcnt(0)
	v_lshl_add_u32 v136, v1, 12, v7
	s_add_u32 s8, s50, 0x80000
	global_load_lds_dwordx4 v136, s[50:51]
	s_addc_u32 s9, s51, 0
	s_add_i32 m0, s54, 0x14000
	s_add_i32 s55, s54, 0x2000
	global_load_lds_dwordx4 v2, s[8:9]
	s_add_i32 m0, s54, 0x16000
	v_lshl_add_u32 v134, v6, 12, v7
	global_load_lds_dwordx4 v136, s[8:9]
	s_mov_b32 m0, s54
	s_add_u32 s8, s48, 0x80000
	global_load_lds_dwordx4 v132, s[48:49]
	s_mov_b32 m0, s55
	s_addc_u32 s9, s49, 0
	s_add_i32 s56, s54, 0x4000
	global_load_lds_dwordx4 v134, s[48:49]
	s_mov_b32 m0, s56
	s_add_i32 s57, s54, 0x6000
	global_load_lds_dwordx4 v132, s[8:9]
	s_mov_b32 m0, s57
	v_mov_b32_e32 v137, v3
	global_load_lds_dwordx4 v134, s[8:9]
	v_mov_b32_e32 v133, v3
	v_mov_b32_e32 v135, v3
	s_cmp_eq_u32 s34, 1
	v_lshl_add_u64 v[12:13], s[50:51], 0, v[2:3]
	v_lshl_add_u64 v[10:11], s[50:51], 0, v[136:137]
	v_lshl_add_u64 v[6:7], s[48:49], 0, v[132:133]
	s_cselect_b64 s[8:9], -1, 0
	s_cmp_lg_u32 s34, 1
	v_lshl_add_u64 v[8:9], s[48:49], 0, v[134:135]
	s_cbranch_scc1 .LBB0_1384
	s_barrier
.LBB0_1384:
	s_add_u32 s18, s18, 0x26456000
	s_addc_u32 s19, s19, 0
	s_lshl_b32 s42, s38, 5
	s_and_b32 s44, s42, 0x60
	s_add_i32 m0, s54, 0x18000
	v_lshl_add_u64 v[12:13], v[12:13], 0, s[20:21]
	s_lshl_b32 s35, s34, 13
	s_lshl_b32 s45, s44, 7
	s_waitcnt vmcnt(2)
	s_barrier
	global_load_lds_dwordx4 v[12:13], off
	v_lshl_add_u64 v[10:11], v[10:11], 0, s[20:21]
	s_add_i32 m0, s54, 0x1a000
	s_add_i32 s58, s54, 0x8000
	s_add_i32 s59, s54, 0xa000
	global_load_lds_dwordx4 v[10:11], off
	v_lshl_add_u64 v[6:7], v[6:7], 0, s[20:21]
	s_mov_b32 m0, s58
	s_add_u32 s42, s50, 0x80080
	global_load_lds_dwordx4 v[6:7], off
	v_lshl_add_u64 v[6:7], v[8:9], 0, s[20:21]
	s_mov_b32 m0, s59
	s_addc_u32 s43, s51, 0
	global_load_lds_dwordx4 v[6:7], off
	s_add_i32 m0, s54, 0x1c000
	v_lshl_add_u64 v[6:7], s[42:43], 0, v[2:3]
	global_load_lds_dwordx4 v[6:7], off
	v_lshl_add_u64 v[6:7], s[42:43], 0, v[136:137]
	s_add_i32 m0, s54, 0x1e000
	s_add_i32 s60, 0, 0x20100
	global_load_lds_dwordx4 v[6:7], off
	v_and_b32_e32 v6, 15, v5
	v_lshrrev_b32_e32 v5, 1, v5
	v_and_b32_e32 v7, 24, v5
	v_lshl_or_b32 v1, s34, 6, v6
	v_lshlrev_b32_e32 v5, 1, v7
	s_lshl_b32 s34, s34, 8
	v_lshl_or_b32 v5, v6, 6, v5
	v_lshlrev_b32_e32 v6, 2, v6
	s_add_i32 s34, s60, s34
	v_and_b32_e32 v8, 32, v6
	s_cmpk_lt_u32 s41, 0x100
	v_bitop3_b32 v9, v5, s35, v8 bitop3:0xde
	v_add_u32_e32 v149, s34, v6
	s_cselect_b64 s[34:35], -1, 0
	s_and_b32 s42, s41, 0xffffffc0
	s_ashr_i32 s43, s42, 31
	s_lshl_b64 s[42:43], s[42:43], 2
	s_add_u32 s42, s39, s42
	v_bitop3_b32 v148, v5, s45, v8 bitop3:0xde
	s_addc_u32 s43, s40, s43
	v_mov_b32_e32 v5, v3
	v_lshl_add_u64 v[138:139], s[42:43], 0, v[4:5]
	v_lshlrev_b32_e32 v4, 15, v17
	v_and_b32_e32 v4, 0xffff0000, v4
	v_lshl_add_u32 v4, v18, 12, v4
	v_and_b32_e32 v5, 1, v17
	v_lshl_or_b32 v4, v5, 6, v4
	s_lshl_b32 s38, s38, 8
	v_lshl_add_u32 v140, v19, 1, v4
	v_lshlrev_b32_e32 v4, 15, v14
	s_add_i32 s60, s60, s38
	v_and_b32_e32 v4, 0xffff0000, v4
	v_readlane_b32 s38, v254, 48
	s_waitcnt vmcnt(6)
	v_lshl_add_u32 v4, v15, 12, v4
	v_and_b32_e32 v5, 1, v14
	v_readlane_b32 s39, v254, 49
	v_lshl_or_b32 v4, v5, 6, v4
	s_mov_b32 s62, s38
	s_sub_i32 s62, 31, s62
	v_readlane_b32 s38, v254, 44
	v_or_b32_e32 v150, s44, v7
	v_mov_b32_e32 v141, v3
	v_lshl_add_u32 v142, v16, 1, v4
	v_mov_b32_e32 v143, v3
	s_mov_b32 s64, 0
	v_add_u32_e32 v151, 0, v9
	s_mov_b32 s63, s38
	s_mov_b64 s[46:47], s[50:51]
	s_mov_b64 s[44:45], s[48:49]
	s_barrier
	v_readlane_b32 s39, v254, 45
	s_branch .LBB0_1387

;     DI bool next(int i, Unit& u) const {
;         const long L = (long)i * G + c; if (L >= (long)nM * nN) return false;
;         xcd_tile<WGM_FULL>((int)L, nM, nN, u.pm, u.pn); u.ks = -1; u.nt = nt;
;         u.a = (const char*)g.A + (size_t)u.pm * BM * g.lda * 2; u.b = (const char*)g.Bt + (size_t)u.pn * BM * g.ldb * 2; return true;
.LBB0_1387:
	s_add_i32 s61, s64, 1
	s_mul_i32 s39, s61, s11
	s_mul_hi_u32 s40, s61, s10
	s_add_i32 s40, s40, s39
	s_mul_i32 s39, s61, s10
	s_add_u32 s52, s39, s2
	s_addc_u32 s53, s40, s3
	v_mov_b64_e32 v[4:5], 0x900
	v_cmp_gt_i64_e32 vcc, s[52:53], v[202:203]
	v_cmp_lt_i64_e64 s[40:41], s[52:53], v[4:5]
	s_cbranch_vccnz .LBB0_1389
	s_ashr_i32 s38, s52, 31
	s_lshr_b32 s38, s38, 29
	s_add_i32 s38, s52, s38
	s_ashr_i32 s39, s38, 3
	s_and_b32 s38, s38, -8
	s_sub_i32 s38, s52, s38
	s_cmp_lt_i32 s38, 0
	s_movk_i32 s42, 0x121
	s_cselect_b32 s42, s42, 0x120
	s_mul_i32 s38, s38, s42
	s_add_i32 s38, s38, s39
	s_ashr_i32 s39, s38, 31
	s_lshr_b32 s39, s39, 24
	s_add_i32 s39, s38, s39
	s_ashr_i32 s42, s39, 8
	s_lshl_b32 s42, s42, 3
	s_sub_i32 s43, 0x48, s42
	s_min_i32 s43, s43, 8
	s_abs_i32 s44, s43
	v_cvt_f32_u32_e32 v4, s44
	s_sub_i32 s46, 0, s44
	s_and_b32 s39, s39, 0xffffff00
	s_sub_i32 s39, s38, s39
	v_rcp_iflag_f32_e32 v4, v4
	s_abs_i32 s38, s39
	s_xor_b32 s45, s39, s43
	s_ashr_i32 s45, s45, 31
	v_mul_f32_e32 v4, 0x4f7ffffe, v4
	v_cvt_u32_f32_e32 v4, v4
	s_nop 0
	v_readfirstlane_b32 s47, v4
	s_mul_i32 s46, s46, s47
	s_mul_hi_u32 s46, s47, s46
	s_add_i32 s47, s47, s46
	s_mul_hi_u32 s46, s38, s47
	s_mul_i32 s47, s46, s44
	s_sub_i32 s38, s38, s47
	s_add_i32 s52, s46, 1
	s_sub_i32 s47, s38, s44
	s_cmp_ge_u32 s38, s44
	s_cselect_b32 s46, s52, s46
	s_cselect_b32 s38, s47, s38
	s_add_i32 s47, s46, 1
	s_cmp_ge_u32 s38, s44
	s_cselect_b32 s38, s47, s46
	s_xor_b32 s38, s38, s45
	s_sub_i32 s38, s38, s45
	s_mul_i32 s43, s38, s43
	s_sub_i32 s39, s39, s43
	s_add_i32 s42, s42, s39
	s_sub_i32 s38, 31, s38
	s_ashr_i32 s43, s42, 31
	s_lshl_b64 s[44:45], s[42:43], 20
	s_add_u32 s44, s12, s44
	s_addc_u32 s45, s22, s45
	s_ashr_i32 s39, s38, 31
	s_lshl_b64 s[46:47], s[38:39], 20
	s_add_u32 s46, s23, s46
	s_addc_u32 s47, s26, s47

; #define PG8_STAGE(bufoff, gbase, voff) do { _Pragma("unroll") for (int _i = 0; _i < 2; ++_i) \
;         __builtin_amdgcn_global_load_lds((const unsigned*)((const char*)(gbase) + (voff)[_i]), (LAS unsigned*)(lds + (bufoff) + ldsw + _i * 8192), 16, 0, 0); } while (0)
; #define PG8_LDA(dst, b, h) do { _Pragma("unroll") for (int m = 0; m < 4; ++m) _Pragma("unroll") for (int k = 0; k < 2; ++k) dst[m][k] = *(const LAS bf16x8*)(lds + PG8_SA(b, h) + aoff + m * 2048 + k * 1024); } while (0)
; #define PG8_LDB(dst, b, h) do { _Pragma("unroll") for (int n = 0; n < 2; ++n) _Pragma("unroll") for (int k = 0; k < 2; ++k) dst[n][k] = *(const LAS bf16x8*)(lds + PG8_SB(b, h) + boff + n * 2048 + k * 1024); } while (0)
; #define PG8_BAR __builtin_amdgcn_s_barrier()
; template <class Epi, class Sched>
; DI void gemm_phase(LAS unsigned char* lds, const Sched& S, const Epi& E) {
;     ...
;         for (int t = 0; t < nt; t += 2) {
;             const bool last = (t == nt - 2);
;             const char* a1 = cA + (size_t)(t + 1) * kstep;
;             const char* a2 = last ? nA : cA + (size_t)(t + 2) * kstep; const char* b2 = last ? nB : cB + (size_t)(t + 2) * kstep;
;             const char* a3 = a2 + kstep; const char* b3 = b2 + kstep;
;             if constexpr (Epi::HOOK) { if (cur.ks < 0 && (t == 16 || t == 32)) E.hook(acc, cur, t >> 4, wr, wc, fr, fq); }
;             PG8_LDB(B0, 0, 0); PG8_LDB(B1, 0, 1); PG8_SCHED; PG8_LDA(At, 0, 0); PG8_STAGE(PG8_SA(1, 1), a1 + hstepA, voffA);
;             PG8_WAIT_V(8); PG8_WAIT_L(0); PG8_BAR; PG8_MMA(0, 0, At, B0); PG8_MMA(0, 1, At, B1); PG8_BAR; PG8_SCHED;
;             PG8_LDA(At, 0, 1); PG8_STAGE(PG8_SB(0, 0), b2, voffB); PG8_STAGE(PG8_SB(0, 1), b2 + hstepB, voffB); PG8_STAGE(PG8_SA(0, 0), a2, voffA);
;             PG8_WAIT_V(8); PG8_WAIT_L(0); PG8_BAR; PG8_MMA(1, 0, At, B0); PG8_MMA(1, 1, At, B1); PG8_BAR; PG8_SCHED;
;             PG8_LDB(B0, 1, 0); PG8_LDB(B1, 1, 1); PG8_SCHED; PG8_LDA(At, 1, 0); PG8_STAGE(PG8_SA(0, 1), a2 + hstepA, voffA);
;             PG8_WAIT_V(8); PG8_WAIT_L(0); PG8_BAR; PG8_MMA(0, 0, At, B0); PG8_MMA(0, 1, At, B1); PG8_BAR; PG8_SCHED;
;             PG8_LDA(At, 1, 1); PG8_STAGE(PG8_SB(1, 0), b3, voffB); PG8_STAGE(PG8_SB(1, 1), b3 + hstepB, voffB); PG8_STAGE(PG8_SA(1, 0), a3, voffA);
;             PG8_WAIT_V(8); PG8_WAIT_L(0); PG8_BAR; PG8_MMA(1, 0, At, B0); PG8_MMA(1, 1, At, B1); PG8_BAR; PG8_SCHED;
.LBB0_1390:
	s_add_u32 s50, s48, 0xfff80080
	s_addc_u32 s51, s49, -1
	s_add_i32 s66, 0, 0x10000
	s_cmp_eq_u32 s65, 28
	s_cselect_b32 s53, s45, s51
	s_cselect_b32 s52, s44, s50
	s_cselect_b32 s51, s47, s43
	s_cselect_b32 s50, s46, s39
	s_add_i32 s71, 0, 0x14000
	v_add_u32_e32 v160, s66, v148
	v_add_u32_e32 v176, s71, v148
	ds_read_b128 v[144:147], v160
	ds_read_b128 v[152:155], v160 offset:1024
	ds_read_b128 v[156:159], v160 offset:2048
	ds_read_b128 v[160:163], v160 offset:3072
	ds_read_b128 v[164:167], v176
	ds_read_b128 v[168:171], v176 offset:1024
	ds_read_b128 v[172:175], v176 offset:2048
	ds_read_b128 v[176:179], v176 offset:3072
	s_add_i32 m0, s54, 0xc000
	ds_read_b128 v[180:183], v151
	ds_read_b128 v[184:187], v151 offset:1024
	ds_read_b128 v[188:191], v151 offset:2048
	ds_read_b128 v[192:195], v151 offset:3072
	ds_read_b128 v[204:207], v151 offset:4096
	ds_read_b128 v[208:211], v151 offset:5120
	ds_read_b128 v[212:215], v151 offset:6144
	ds_read_b128 v[230:233], v151 offset:7168
	global_load_lds_dwordx4 v142, s[48:49]
	s_add_i32 m0, s54, 0xe000
	s_nop 0
	global_load_lds_dwordx4 v140, s[48:49]
	s_waitcnt vmcnt(8)
	s_waitcnt lgkmcnt(0)
	s_barrier
	s_setprio 1
	s_waitcnt lgkmcnt(0)
	v_mfma_f32_16x16x32_bf16 v[128:131], v[144:147], v[180:183], v[128:131]
	v_mfma_f32_16x16x32_bf16 v[124:127], v[156:159], v[180:183], v[124:127]
	v_mfma_f32_16x16x32_bf16 v[112:115], v[144:147], v[188:191], v[112:115]
	v_mfma_f32_16x16x32_bf16 v[108:111], v[156:159], v[188:191], v[108:111]
	v_mfma_f32_16x16x32_bf16 v[96:99], v[144:147], v[204:207], v[96:99]
	v_mfma_f32_16x16x32_bf16 v[92:95], v[156:159], v[204:207], v[92:95]
	v_mfma_f32_16x16x32_bf16 v[80:83], v[144:147], v[212:215], v[80:83]
	v_mfma_f32_16x16x32_bf16 v[76:79], v[156:159], v[212:215], v[76:79]
	v_mfma_f32_16x16x32_bf16 v[128:131], v[152:155], v[184:187], v[128:131]
	v_mfma_f32_16x16x32_bf16 v[124:127], v[160:163], v[184:187], v[124:127]
	v_mfma_f32_16x16x32_bf16 v[112:115], v[152:155], v[192:195], v[112:115]
	v_mfma_f32_16x16x32_bf16 v[108:111], v[160:163], v[192:195], v[108:111]
	v_mfma_f32_16x16x32_bf16 v[96:99], v[152:155], v[208:211], v[96:99]
	v_mfma_f32_16x16x32_bf16 v[92:95], v[160:163], v[208:211], v[92:95]
	v_mfma_f32_16x16x32_bf16 v[80:83], v[152:155], v[230:233], v[80:83]
	v_mfma_f32_16x16x32_bf16 v[76:79], v[160:163], v[230:233], v[76:79]
	s_setprio 0
	s_setprio 1
	v_mfma_f32_16x16x32_bf16 v[120:123], v[164:167], v[180:183], v[120:123]
	v_mfma_f32_16x16x32_bf16 v[116:119], v[172:175], v[180:183], v[116:119]
	v_mfma_f32_16x16x32_bf16 v[104:107], v[164:167], v[188:191], v[104:107]
	v_mfma_f32_16x16x32_bf16 v[100:103], v[172:175], v[188:191], v[100:103]
	v_mfma_f32_16x16x32_bf16 v[88:91], v[164:167], v[204:207], v[88:91]
	v_mfma_f32_16x16x32_bf16 v[84:87], v[172:175], v[204:207], v[84:87]
	v_mfma_f32_16x16x32_bf16 v[72:75], v[164:167], v[212:215], v[72:75]
	v_mfma_f32_16x16x32_bf16 v[68:71], v[172:175], v[212:215], v[68:71]
	v_mfma_f32_16x16x32_bf16 v[120:123], v[168:171], v[184:187], v[120:123]
	v_mfma_f32_16x16x32_bf16 v[116:119], v[176:179], v[184:187], v[116:119]
	v_mfma_f32_16x16x32_bf16 v[104:107], v[168:171], v[192:195], v[104:107]
	v_mfma_f32_16x16x32_bf16 v[100:103], v[176:179], v[192:195], v[100:103]
	v_mfma_f32_16x16x32_bf16 v[88:91], v[168:171], v[208:211], v[88:91]
	v_mfma_f32_16x16x32_bf16 v[84:87], v[176:179], v[208:211], v[84:87]
	v_mfma_f32_16x16x32_bf16 v[72:75], v[168:171], v[230:233], v[72:75]
	v_mfma_f32_16x16x32_bf16 v[68:71], v[176:179], v[230:233], v[68:71]
	s_setprio 0
	s_barrier
	s_add_i32 s66, s66, s27
	s_mov_b32 m0, s66
	ds_read_b128 v[180:183], v151 offset:16384
	ds_read_b128 v[184:187], v151 offset:17408
	ds_read_b128 v[188:191], v151 offset:18432
	ds_read_b128 v[192:195], v151 offset:19456
	ds_read_b128 v[204:207], v151 offset:20480
	ds_read_b128 v[208:211], v151 offset:21504
	ds_read_b128 v[212:215], v151 offset:22528
	ds_read_b128 v[230:233], v151 offset:23552
	global_load_lds_dwordx4 v2, s[50:51]
	s_add_i32 m0, s66, 0x2000
	s_add_u32 s66, s50, 0x80000
	s_addc_u32 s67, s51, 0
	s_add_i32 s71, s71, s27
	global_load_lds_dwordx4 v136, s[50:51]
	s_mov_b32 m0, s71
	s_add_u32 s86, s52, 0x80
	s_addc_u32 s87, s53, 0
	global_load_lds_dwordx4 v2, s[66:67]
	s_add_i32 m0, s71, 0x2000
	s_nop 0
	global_load_lds_dwordx4 v136, s[66:67]
	s_mov_b32 m0, s54
	s_nop 0
	global_load_lds_dwordx4 v132, s[52:53]
	s_mov_b32 m0, s55
	s_nop 0
	global_load_lds_dwordx4 v134, s[52:53]
	s_waitcnt vmcnt(8)
	s_waitcnt lgkmcnt(0)
	s_barrier
	s_setprio 1
	s_waitcnt lgkmcnt(0)
	v_mfma_f32_16x16x32_bf16 v[64:67], v[144:147], v[180:183], v[64:67]
	v_mfma_f32_16x16x32_bf16 v[60:63], v[156:159], v[180:183], v[60:63]
	v_mfma_f32_16x16x32_bf16 v[48:51], v[144:147], v[188:191], v[48:51]
	v_mfma_f32_16x16x32_bf16 v[44:47], v[156:159], v[188:191], v[44:47]
	v_mfma_f32_16x16x32_bf16 v[32:35], v[144:147], v[204:207], v[32:35]
	v_mfma_f32_16x16x32_bf16 v[28:31], v[156:159], v[204:207], v[28:31]
	v_mfma_f32_16x16x32_bf16 v[16:19], v[144:147], v[212:215], v[16:19]
	v_mfma_f32_16x16x32_bf16 v[12:15], v[156:159], v[212:215], v[12:15]
	v_mfma_f32_16x16x32_bf16 v[64:67], v[152:155], v[184:187], v[64:67]
	v_mfma_f32_16x16x32_bf16 v[60:63], v[160:163], v[184:187], v[60:63]
	v_mfma_f32_16x16x32_bf16 v[48:51], v[152:155], v[192:195], v[48:51]
	v_mfma_f32_16x16x32_bf16 v[44:47], v[160:163], v[192:195], v[44:47]
	v_mfma_f32_16x16x32_bf16 v[32:35], v[152:155], v[208:211], v[32:35]
	v_mfma_f32_16x16x32_bf16 v[28:31], v[160:163], v[208:211], v[28:31]
	v_mfma_f32_16x16x32_bf16 v[16:19], v[152:155], v[230:233], v[16:19]
	v_mfma_f32_16x16x32_bf16 v[12:15], v[160:163], v[230:233], v[12:15]
	s_setprio 0
	s_setprio 1
	v_mfma_f32_16x16x32_bf16 v[56:59], v[164:167], v[180:183], v[56:59]
	v_mfma_f32_16x16x32_bf16 v[52:55], v[172:175], v[180:183], v[52:55]
	v_mfma_f32_16x16x32_bf16 v[40:43], v[164:167], v[188:191], v[40:43]
	v_mfma_f32_16x16x32_bf16 v[36:39], v[172:175], v[188:191], v[36:39]
	v_mfma_f32_16x16x32_bf16 v[24:27], v[164:167], v[204:207], v[24:27]
	v_mfma_f32_16x16x32_bf16 v[20:23], v[172:175], v[204:207], v[20:23]
	v_mfma_f32_16x16x32_bf16 v[8:11], v[164:167], v[212:215], v[8:11]
	v_mfma_f32_16x16x32_bf16 v[4:7], v[172:175], v[212:215], v[4:7]
	v_mfma_f32_16x16x32_bf16 v[56:59], v[168:171], v[184:187], v[56:59]
	v_mfma_f32_16x16x32_bf16 v[52:55], v[176:179], v[184:187], v[52:55]
	v_mfma_f32_16x16x32_bf16 v[40:43], v[168:171], v[192:195], v[40:43]
	v_mfma_f32_16x16x32_bf16 v[36:39], v[176:179], v[192:195], v[36:39]
	v_mfma_f32_16x16x32_bf16 v[24:27], v[168:171], v[208:211], v[24:27]
	v_mfma_f32_16x16x32_bf16 v[20:23], v[176:179], v[208:211], v[20:23]
	v_mfma_f32_16x16x32_bf16 v[8:11], v[168:171], v[230:233], v[8:11]
	v_mfma_f32_16x16x32_bf16 v[4:7], v[176:179], v[230:233], v[4:7]
	s_setprio 0
	s_barrier
; #define PG8_STAGE(bufoff, gbase, voff) do { _Pragma("unroll") for (int _i = 0; _i < 2; ++_i) \
;         __builtin_amdgcn_global_load_lds((const unsigned*)((const char*)(gbase) + (voff)[_i]), (LAS unsigned*)(lds + (bufoff) + ldsw + _i * 8192), 16, 0, 0); } while (0)
; #define PG8_LDA(dst, b, h) do { _Pragma("unroll") for (int m = 0; m < 4; ++m) _Pragma("unroll") for (int k = 0; k < 2; ++k) dst[m][k] = *(const LAS bf16x8*)(lds + PG8_SA(b, h) + aoff + m * 2048 + k * 1024); } while (0)
; #define PG8_LDB(dst, b, h) do { _Pragma("unroll") for (int n = 0; n < 2; ++n) _Pragma("unroll") for (int k = 0; k < 2; ++k) dst[n][k] = *(const LAS bf16x8*)(lds + PG8_SB(b, h) + boff + n * 2048 + k * 1024); } while (0)
; #define PG8_BAR __builtin_amdgcn_s_barrier()
; template <class Epi, class Sched>
; DI void gemm_phase(LAS unsigned char* lds, const Sched& S, const Epi& E) {
;     ...
;         for (int t = 0; t < nt; t += 2) {
;             const bool last = (t == nt - 2);
;             const char* a1 = cA + (size_t)(t + 1) * kstep;
;             const char* a2 = last ? nA : cA + (size_t)(t + 2) * kstep; const char* b2 = last ? nB : cB + (size_t)(t + 2) * kstep;
;             const char* a3 = a2 + kstep; const char* b3 = b2 + kstep;
;             if constexpr (Epi::HOOK) { if (cur.ks < 0 && (t == 16 || t == 32)) E.hook(acc, cur, t >> 4, wr, wc, fr, fq); }
;             PG8_LDB(B0, 0, 0); PG8_LDB(B1, 0, 1); PG8_SCHED; PG8_LDA(At, 0, 0); PG8_STAGE(PG8_SA(1, 1), a1 + hstepA, voffA);
;             PG8_WAIT_V(8); PG8_WAIT_L(0); PG8_BAR; PG8_MMA(0, 0, At, B0); PG8_MMA(0, 1, At, B1); PG8_BAR; PG8_SCHED;
;             PG8_LDA(At, 0, 1); PG8_STAGE(PG8_SB(0, 0), b2, voffB); PG8_STAGE(PG8_SB(0, 1), b2 + hstepB, voffB); PG8_STAGE(PG8_SA(0, 0), a2, voffA);
;             PG8_WAIT_V(8); PG8_WAIT_L(0); PG8_BAR; PG8_MMA(1, 0, At, B0); PG8_MMA(1, 1, At, B1); PG8_BAR; PG8_SCHED;
;             PG8_LDB(B0, 1, 0); PG8_LDB(B1, 1, 1); PG8_SCHED; PG8_LDA(At, 1, 0); PG8_STAGE(PG8_SA(0, 1), a2 + hstepA, voffA);
;             PG8_WAIT_V(8); PG8_WAIT_L(0); PG8_BAR; PG8_MMA(0, 0, At, B0); PG8_MMA(0, 1, At, B1); PG8_BAR; PG8_SCHED;
;             PG8_LDA(At, 1, 1); PG8_STAGE(PG8_SB(1, 0), b3, voffB); PG8_STAGE(PG8_SB(1, 1), b3 + hstepB, voffB); PG8_STAGE(PG8_SA(1, 0), a3, voffA);
;             PG8_WAIT_V(8); PG8_WAIT_L(0); PG8_BAR; PG8_MMA(1, 0, At, B0); PG8_MMA(1, 1, At, B1); PG8_BAR; PG8_SCHED;
	s_add_i32 s66, 0, 0x18000
	s_add_i32 s67, 0, 0x1c000
	v_add_u32_e32 v160, s66, v148
	v_add_u32_e32 v176, s67, v148
	ds_read_b128 v[144:147], v160
	ds_read_b128 v[152:155], v160 offset:1024
	ds_read_b128 v[156:159], v160 offset:2048
	ds_read_b128 v[160:163], v160 offset:3072
	ds_read_b128 v[164:167], v176
	ds_read_b128 v[168:171], v176 offset:1024
	ds_read_b128 v[172:175], v176 offset:2048
	ds_read_b128 v[176:179], v176 offset:3072
	s_add_u32 s52, s52, 0x80000
	s_addc_u32 s53, s53, 0
	s_mov_b32 m0, s56
	ds_read_b128 v[180:183], v151 offset:32768
	ds_read_b128 v[184:187], v151 offset:33792
	ds_read_b128 v[188:191], v151 offset:34816
	ds_read_b128 v[192:195], v151 offset:35840
	ds_read_b128 v[204:207], v151 offset:36864
	ds_read_b128 v[208:211], v151 offset:37888
	ds_read_b128 v[212:215], v151 offset:38912
	ds_read_b128 v[230:233], v151 offset:39936
	global_load_lds_dwordx4 v132, s[52:53]
	s_mov_b32 m0, s57
	s_nop 0
	global_load_lds_dwordx4 v134, s[52:53]
	s_waitcnt vmcnt(8)
	s_waitcnt lgkmcnt(0)
	s_barrier
	s_setprio 1
	s_waitcnt lgkmcnt(0)
	v_mfma_f32_16x16x32_bf16 v[128:131], v[144:147], v[180:183], v[128:131]
	v_mfma_f32_16x16x32_bf16 v[124:127], v[156:159], v[180:183], v[124:127]
	v_mfma_f32_16x16x32_bf16 v[112:115], v[144:147], v[188:191], v[112:115]
	v_mfma_f32_16x16x32_bf16 v[108:111], v[156:159], v[188:191], v[108:111]
	v_mfma_f32_16x16x32_bf16 v[96:99], v[144:147], v[204:207], v[96:99]
	v_mfma_f32_16x16x32_bf16 v[92:95], v[156:159], v[204:207], v[92:95]
	v_mfma_f32_16x16x32_bf16 v[80:83], v[144:147], v[212:215], v[80:83]
	v_mfma_f32_16x16x32_bf16 v[76:79], v[156:159], v[212:215], v[76:79]
	v_mfma_f32_16x16x32_bf16 v[128:131], v[152:155], v[184:187], v[128:131]
	v_mfma_f32_16x16x32_bf16 v[124:127], v[160:163], v[184:187], v[124:127]
	v_mfma_f32_16x16x32_bf16 v[112:115], v[152:155], v[192:195], v[112:115]
	v_mfma_f32_16x16x32_bf16 v[108:111], v[160:163], v[192:195], v[108:111]
	v_mfma_f32_16x16x32_bf16 v[96:99], v[152:155], v[208:211], v[96:99]
	v_mfma_f32_16x16x32_bf16 v[92:95], v[160:163], v[208:211], v[92:95]
	v_mfma_f32_16x16x32_bf16 v[80:83], v[152:155], v[230:233], v[80:83]
	v_mfma_f32_16x16x32_bf16 v[76:79], v[160:163], v[230:233], v[76:79]
	s_setprio 0
	s_setprio 1
	v_mfma_f32_16x16x32_bf16 v[120:123], v[164:167], v[180:183], v[120:123]
	v_mfma_f32_16x16x32_bf16 v[116:119], v[172:175], v[180:183], v[116:119]
	v_mfma_f32_16x16x32_bf16 v[104:107], v[164:167], v[188:191], v[104:107]
	v_mfma_f32_16x16x32_bf16 v[100:103], v[172:175], v[188:191], v[100:103]
	v_mfma_f32_16x16x32_bf16 v[88:91], v[164:167], v[204:207], v[88:91]
	v_mfma_f32_16x16x32_bf16 v[84:87], v[172:175], v[204:207], v[84:87]
	v_mfma_f32_16x16x32_bf16 v[72:75], v[164:167], v[212:215], v[72:75]
	v_mfma_f32_16x16x32_bf16 v[68:71], v[172:175], v[212:215], v[68:71]
	v_mfma_f32_16x16x32_bf16 v[120:123], v[168:171], v[184:187], v[120:123]
	v_mfma_f32_16x16x32_bf16 v[116:119], v[176:179], v[184:187], v[116:119]
	v_mfma_f32_16x16x32_bf16 v[104:107], v[168:171], v[192:195], v[104:107]
	v_mfma_f32_16x16x32_bf16 v[100:103], v[176:179], v[192:195], v[100:103]
	v_mfma_f32_16x16x32_bf16 v[88:91], v[168:171], v[208:211], v[88:91]
	v_mfma_f32_16x16x32_bf16 v[84:87], v[176:179], v[208:211], v[84:87]
	v_mfma_f32_16x16x32_bf16 v[72:75], v[168:171], v[230:233], v[72:75]
	v_mfma_f32_16x16x32_bf16 v[68:71], v[176:179], v[230:233], v[68:71]
	s_setprio 0
	s_barrier
	s_add_i32 s52, s66, s27
	s_add_u32 s50, s50, 0x80
	s_addc_u32 s51, s51, 0
	s_mov_b32 m0, s52
	ds_read_b128 v[180:183], v151 offset:49152
	ds_read_b128 v[184:187], v151 offset:50176
	ds_read_b128 v[188:191], v151 offset:51200
	ds_read_b128 v[192:195], v151 offset:52224
	ds_read_b128 v[204:207], v151 offset:53248
	ds_read_b128 v[208:211], v151 offset:54272
	ds_read_b128 v[212:215], v151 offset:55296
	ds_read_b128 v[230:233], v151 offset:56320
	global_load_lds_dwordx4 v2, s[50:51]
	s_add_i32 m0, s52, 0x2000
	s_add_i32 s52, s67, s27
	global_load_lds_dwordx4 v136, s[50:51]
	s_add_u32 s50, s50, 0x80000
	s_addc_u32 s51, s51, 0
	s_mov_b32 m0, s52
	s_nop 0
	global_load_lds_dwordx4 v2, s[50:51]
	s_add_i32 m0, s52, 0x2000
	s_nop 0
	global_load_lds_dwordx4 v136, s[50:51]
	s_mov_b32 m0, s58
	s_nop 0
	global_load_lds_dwordx4 v132, s[86:87]
	s_mov_b32 m0, s59
	s_nop 0
	global_load_lds_dwordx4 v134, s[86:87]
	s_waitcnt vmcnt(8)
	s_waitcnt lgkmcnt(0)
	s_barrier
	s_setprio 1
	s_waitcnt lgkmcnt(0)
	v_mfma_f32_16x16x32_bf16 v[64:67], v[144:147], v[180:183], v[64:67]
	v_mfma_f32_16x16x32_bf16 v[60:63], v[156:159], v[180:183], v[60:63]
	v_mfma_f32_16x16x32_bf16 v[48:51], v[144:147], v[188:191], v[48:51]
	v_mfma_f32_16x16x32_bf16 v[44:47], v[156:159], v[188:191], v[44:47]
	v_mfma_f32_16x16x32_bf16 v[32:35], v[144:147], v[204:207], v[32:35]
	v_mfma_f32_16x16x32_bf16 v[28:31], v[156:159], v[204:207], v[28:31]
	v_mfma_f32_16x16x32_bf16 v[16:19], v[144:147], v[212:215], v[16:19]
	v_mfma_f32_16x16x32_bf16 v[12:15], v[156:159], v[212:215], v[12:15]
	v_mfma_f32_16x16x32_bf16 v[64:67], v[152:155], v[184:187], v[64:67]
	v_mfma_f32_16x16x32_bf16 v[60:63], v[160:163], v[184:187], v[60:63]
	v_mfma_f32_16x16x32_bf16 v[48:51], v[152:155], v[192:195], v[48:51]
	v_mfma_f32_16x16x32_bf16 v[44:47], v[160:163], v[192:195], v[44:47]
	v_mfma_f32_16x16x32_bf16 v[32:35], v[152:155], v[208:211], v[32:35]
	v_mfma_f32_16x16x32_bf16 v[28:31], v[160:163], v[208:211], v[28:31]
	v_mfma_f32_16x16x32_bf16 v[16:19], v[152:155], v[230:233], v[16:19]
	v_mfma_f32_16x16x32_bf16 v[12:15], v[160:163], v[230:233], v[12:15]
	s_setprio 0
	s_setprio 1
	v_mfma_f32_16x16x32_bf16 v[56:59], v[164:167], v[180:183], v[56:59]
	v_mfma_f32_16x16x32_bf16 v[52:55], v[172:175], v[180:183], v[52:55]
	v_mfma_f32_16x16x32_bf16 v[40:43], v[164:167], v[188:191], v[40:43]
	v_mfma_f32_16x16x32_bf16 v[36:39], v[172:175], v[188:191], v[36:39]
	v_mfma_f32_16x16x32_bf16 v[24:27], v[164:167], v[204:207], v[24:27]
	v_mfma_f32_16x16x32_bf16 v[20:23], v[172:175], v[204:207], v[20:23]
	v_mfma_f32_16x16x32_bf16 v[8:11], v[164:167], v[212:215], v[8:11]
	v_mfma_f32_16x16x32_bf16 v[4:7], v[172:175], v[212:215], v[4:7]
	v_mfma_f32_16x16x32_bf16 v[56:59], v[168:171], v[184:187], v[56:59]
	v_mfma_f32_16x16x32_bf16 v[52:55], v[176:179], v[184:187], v[52:55]
	v_mfma_f32_16x16x32_bf16 v[40:43], v[168:171], v[192:195], v[40:43]
	v_mfma_f32_16x16x32_bf16 v[36:39], v[176:179], v[192:195], v[36:39]
	v_mfma_f32_16x16x32_bf16 v[24:27], v[168:171], v[208:211], v[24:27]
	v_mfma_f32_16x16x32_bf16 v[20:23], v[176:179], v[208:211], v[20:23]
	v_mfma_f32_16x16x32_bf16 v[8:11], v[168:171], v[230:233], v[8:11]
	v_mfma_f32_16x16x32_bf16 v[4:7], v[176:179], v[230:233], v[4:7]
	s_setprio 0
	s_barrier
	s_add_i32 s65, s65, 2
	s_add_u32 s39, s39, 0x100
	s_addc_u32 s43, s43, 0
	s_add_u32 s48, s48, 0x100
	s_addc_u32 s49, s49, 0
	s_cmp_gt_u32 s65, 29
	s_cbranch_scc0 .LBB0_1390
	s_and_b64 vcc, exec, s[34:35]
	s_cbranch_vccz .LBB0_1393
	s_barrier
